# split-phase seams: H2->QKV and combine->P3 barriers arrive early (own counters, XCC leader writes L2 back) and are waited for just before the next GEMM's first epilogue store
# speedup vs baseline: 1.0178x; 1.0117x over previous
_Z6mk_fwd4Args:
	s_mov_b32 s100, 0
	s_mov_b32 s74, s2
	s_load_dword s2, s[0:1], 0x98
	s_load_dwordx4 s[76:79], s[0:1], 0x80
	s_load_dwordx2 s[52:53], s[0:1], 0x90
	s_add_u32 s4, s0, 0x90
	v_and_b32_e32 v171, 0x3ff, v0
	s_addc_u32 s5, s1, 0
	v_readfirstlane_b32 s48, v171
	v_cmp_gt_u32_e32 vcc, 2, v171
	s_waitcnt lgkmcnt(0)
	v_writelane_b32 v246, s2, 0
	s_and_saveexec_b64 s[2:3], vcc
	v_lshl_add_u32 v1, v171, 2, 0
	v_add_u32_e32 v1, 0x20000, v1
	v_mov_b32_e32 v2, 0
	ds_write_b32 v1, v2
	s_or_b64 exec, exec, s[2:3]
	s_add_u32 s2, s76, 0x280000
	s_addc_u32 s3, s77, 0
	v_writelane_b32 v246, s2, 1
	s_sub_i32 s10, s79, s78
	s_cmp_lt_i32 s10, 2
	v_writelane_b32 v246, s3, 2
	s_mov_b32 s2, 0
	v_cmp_eq_u32_e32 vcc, 0, v171
	s_waitcnt lgkmcnt(0)
	s_barrier
	v_writelane_b32 v246, s2, 3
	s_cbranch_scc1 .LBB0_7
	s_getreg_b32 s2, hwreg(HW_REG_XCC_ID, 0, 4)
	s_and_b32 s2, s2, 15
	v_writelane_b32 v246, s2, 3
	s_and_saveexec_b64 s[2:3], vcc
	s_cbranch_execz .LBB0_6
	s_mov_b64 s[6:7], exec
	v_mbcnt_lo_u32_b32 v1, s6, 0
	v_mbcnt_hi_u32_b32 v1, s7, v1
	v_cmp_eq_u32_e32 vcc, 0, v1
	s_and_b64 s[8:9], exec, vcc
	s_mov_b64 exec, s[8:9]
	s_cbranch_execz .LBB0_6
	v_readlane_b32 s8, v246, 3
	s_bcnt1_i32_b64 s6, s[6:7]
	s_lshl_b32 s8, s8, 8
	v_mov_b32_e32 v2, s6
	v_readlane_b32 s6, v246, 1
	v_mov_b32_e32 v1, s8
	v_readlane_b32 s7, v246, 2
	s_nop 4
	global_atomic_add v1, v2, s[6:7] offset:1024
	v_readlane_b32 s8, v246, 3
	s_and_b32 s9, s74, 7
	s_lshl_b32 s9, s9, 2
	s_addk_i32 s9, 0x3700
	v_mov_b32_e32 v1, s9
	s_add_i32 s9, s8, 1
	v_mov_b32_e32 v2, s9
	s_sub_i32 s8, 16, s8
	v_mov_b32_e32 v3, s8
	global_atomic_umax v1, v2, s[6:7]
	global_atomic_umax v1, v3, s[6:7] offset:256

.LBB0_397:
	s_cmp_gt_i32 s79, 4
	s_cselect_b64 s[0:1], -1, 0
	s_and_b64 s[2:3], s[2:3], s[0:1]
	s_andn2_b64 vcc, exec, s[2:3]
	s_cbranch_vccnz .LBB0_447
	s_and_b64 vcc, exec, s[92:93]
	s_cbranch_vccz .Ldf3_orig
	s_waitcnt vmcnt(0)
	s_barrier
	s_mov_b32 s100, 1
	v_cmp_eq_u32_e32 vcc, 0, v171
	s_and_saveexec_b64 s[98:99], vcc
	s_cbranch_execz .Ldf3_arr
	v_mov_b32_e32 v247, 0x20000
	ds_read_b32 v248, v247
	v_readlane_b32 s96, v246, 1
	v_readlane_b32 s97, v246, 2
	v_readlane_b32 s101, v246, 3
	s_lshl_b32 s101, s101, 2
	s_addk_i32 s101, 0x3900
	v_mov_b32_e32 v249, s101
	v_mov_b32_e32 v250, 1
	s_nop 2
	global_atomic_add v251, v249, v250, s[96:97] sc0
	s_waitcnt vmcnt(0) lgkmcnt(0)
	v_add_u32_e32 v251, 1, v251
	v_cmp_eq_u32_e32 vcc, v251, v248
	s_cbranch_vccz .Ldf3_arr
	buffer_wbl2 sc1
	s_waitcnt vmcnt(0)
	v_mov_b32_e32 v249, 0x3940
	global_atomic_add v249, v250, s[96:97]
.Ldf3_arr:
	s_or_b64 exec, exec, s[98:99]
	s_branch .LBB0_447
.Ldf3_orig:
	s_waitcnt vmcnt(0)
	v_cmp_eq_u32_e32 vcc, 0, v171
	s_waitcnt vmcnt(0)
	s_barrier
	s_and_saveexec_b64 s[2:3], vcc
	s_cbranch_execz .LBB0_446
	s_add_i32 s4, 0, 0x20000
	v_mov_b32_e32 v0, s4
	s_waitcnt vmcnt(0) expcnt(0) lgkmcnt(0)
	ds_read_b32 v2, v0
	s_add_i32 s4, 0, 0x20004
	v_mov_b32_e32 v0, s4
	ds_read_b32 v0, v0
	s_waitcnt lgkmcnt(1)
	v_cmp_ne_u32_e32 vcc, 0, v2
	s_cbranch_vccnz .LBB0_414
	v_readlane_b32 s6, v246, 48
	v_readlane_b32 s4, v246, 0
	v_readlane_b32 s7, v246, 49
	s_mul_i32 s33, s7, s4
	s_add_u32 s4, s76, 0x280200
	s_addc_u32 s5, s77, 0
	s_mul_i32 s33, s33, s6
	s_add_u32 s6, s76, 0x280400
	s_addc_u32 s7, s77, 0
	s_add_u32 s8, s76, 0x280500
	s_addc_u32 s9, s77, 0
	s_add_u32 s10, s76, 0x280600
	s_addc_u32 s11, s77, 0
	s_add_u32 s12, s76, 0x280700
	s_addc_u32 s13, s77, 0
	s_add_u32 s14, s76, 0x280800
	s_addc_u32 s15, s77, 0
	s_add_u32 s16, s76, 0x280900
	s_addc_u32 s17, s77, 0
	s_add_u32 s18, s76, 0x280a00
	s_addc_u32 s19, s77, 0
	s_add_u32 s20, s76, 0x280b00
	s_addc_u32 s21, s77, 0
	s_add_u32 s22, s76, 0x280c00
	s_addc_u32 s23, s77, 0
	s_add_u32 s24, s76, 0x280d00
	s_addc_u32 s25, s77, 0
	s_add_u32 s26, s76, 0x280e00
	s_addc_u32 s27, s77, 0
	s_add_u32 s28, s76, 0x280f00
	s_addc_u32 s29, s77, 0
	s_add_u32 s30, s76, 0x281000
	s_addc_u32 s31, s77, 0
	s_add_u32 s34, s76, 0x281100
	s_addc_u32 s35, s77, 0
	s_add_u32 s36, s76, 0x281200
	s_addc_u32 s37, s77, 0
	s_add_u32 s38, s76, 0x281300
	s_addc_u32 s39, s77, 0
	s_mov_b32 s46, 1
	v_mov_b32_e32 v16, 0
	s_branch .LBB0_402

.LBB0_460:
	s_cmp_eq_u32 s100, 1
	s_cbranch_scc0 .Ldf3_wd
	s_mov_b32 s100, 0
	v_cmp_eq_u32_e64 s[98:99], 0, v171
	s_nop 1
	s_and_saveexec_b64 s[98:99], s[98:99]
	s_cbranch_execz .Ldf3_wj
	v_mov_b32_e32 v247, 0x20004
	ds_read_b32 v248, v247
	v_readlane_b32 s96, v246, 1
	v_readlane_b32 s97, v246, 2
	v_mov_b32_e32 v249, 0x3940
	s_mov_b32 s90, 0
	s_waitcnt lgkmcnt(0)
	v_readfirstlane_b32 s101, v248
	s_nop 3
.Ldf3_poll:
	global_load_dword v250, v249, s[96:97] sc1
	s_waitcnt vmcnt(0)
	v_readfirstlane_b32 s91, v250
	s_nop 0
	s_cmp_ge_u32 s91, s101
	s_cbranch_scc1 .Ldf3_ok
	s_sleep 1
	s_add_i32 s90, s90, 1
	s_cmp_lt_u32 s90, 0x40000
	s_cbranch_scc1 .Ldf3_poll
.Ldf3_ok:
	buffer_inv sc1
	s_waitcnt vmcnt(0)
.Ldf3_wj:
	s_or_b64 exec, exec, s[98:99]
	s_barrier

.LBB0_588:
	s_cmp_gt_i32 s79, 7
	s_cselect_b64 s[0:1], -1, 0
	s_and_b64 s[2:3], s[2:3], s[0:1]
	s_andn2_b64 vcc, exec, s[2:3]
	s_cbranch_vccnz .LBB0_638
	s_and_b64 vcc, exec, s[92:93]
	s_cbranch_vccz .Ldf6_orig
	s_waitcnt vmcnt(0)
	s_barrier
	s_mov_b32 s100, 1
	v_cmp_eq_u32_e32 vcc, 0, v171
	s_and_saveexec_b64 s[98:99], vcc
	s_cbranch_execz .Ldf6_arr
	v_mov_b32_e32 v247, 0x20000
	ds_read_b32 v248, v247
	v_readlane_b32 s96, v246, 1
	v_readlane_b32 s97, v246, 2
	v_readlane_b32 s101, v246, 3
	s_lshl_b32 s101, s101, 2
	s_addk_i32 s101, 0x3980
	v_mov_b32_e32 v249, s101
	v_mov_b32_e32 v250, 1
	s_nop 2
	global_atomic_add v251, v249, v250, s[96:97] sc0
	s_waitcnt vmcnt(0) lgkmcnt(0)
	v_add_u32_e32 v251, 1, v251
	v_cmp_eq_u32_e32 vcc, v251, v248
	s_cbranch_vccz .Ldf6_arr
	buffer_wbl2 sc1
	s_waitcnt vmcnt(0)
	v_mov_b32_e32 v249, 0x39c0
	global_atomic_add v249, v250, s[96:97]

.Ldf6_orig:
	s_waitcnt vmcnt(0)
	v_cmp_eq_u32_e32 vcc, 0, v171
	s_waitcnt vmcnt(0)
	s_barrier
	s_and_saveexec_b64 s[2:3], vcc
	s_cbranch_execz .LBB0_637
	s_add_i32 s4, 0, 0x20000
	v_mov_b32_e32 v0, s4
	s_waitcnt vmcnt(0) expcnt(0) lgkmcnt(0)
	ds_read_b32 v2, v0
	s_add_i32 s4, 0, 0x20004
	v_mov_b32_e32 v0, s4
	ds_read_b32 v0, v0
	s_waitcnt lgkmcnt(1)
	v_cmp_ne_u32_e32 vcc, 0, v2
	s_cbranch_vccnz .LBB0_605
	v_readlane_b32 s6, v246, 48
	v_readlane_b32 s4, v246, 0
	v_readlane_b32 s7, v246, 49
	s_mul_i32 s33, s7, s4
	s_add_u32 s4, s76, 0x280200
	s_addc_u32 s5, s77, 0
	s_mul_i32 s33, s33, s6
	s_add_u32 s6, s76, 0x280400
	s_addc_u32 s7, s77, 0
	s_add_u32 s8, s76, 0x280500
	s_addc_u32 s9, s77, 0
	s_add_u32 s10, s76, 0x280600
	s_addc_u32 s11, s77, 0
	s_add_u32 s12, s76, 0x280700
	s_addc_u32 s13, s77, 0
	s_add_u32 s14, s76, 0x280800
	s_addc_u32 s15, s77, 0
	s_add_u32 s16, s76, 0x280900
	s_addc_u32 s17, s77, 0
	s_add_u32 s18, s76, 0x280a00
	s_addc_u32 s19, s77, 0
	s_add_u32 s20, s76, 0x280b00
	s_addc_u32 s21, s77, 0
	s_add_u32 s22, s76, 0x280c00
	s_addc_u32 s23, s77, 0
	s_add_u32 s24, s76, 0x280d00
	s_addc_u32 s25, s77, 0
	s_add_u32 s26, s76, 0x280e00
	s_addc_u32 s27, s77, 0
	s_add_u32 s28, s76, 0x280f00
	s_addc_u32 s29, s77, 0
	s_add_u32 s34, s76, 0x281000
	s_addc_u32 s35, s77, 0
	s_add_u32 s36, s76, 0x281100
	s_addc_u32 s37, s77, 0
	s_add_u32 s38, s76, 0x281200
	s_addc_u32 s39, s77, 0
	s_add_u32 s40, s76, 0x281300
	s_addc_u32 s41, s77, 0
	s_mov_b32 s48, 1
	v_mov_b32_e32 v16, 0
	s_branch .LBB0_593

.LBB0_649:
	s_cmp_eq_u32 s100, 1
	s_cbranch_scc0 .Ldf6_wd
	s_mov_b32 s100, 0
	v_cmp_eq_u32_e64 s[98:99], 0, v171
	s_nop 1
	s_and_saveexec_b64 s[98:99], s[98:99]
	s_cbranch_execz .Ldf6_wj
	v_mov_b32_e32 v247, 0x20004
	ds_read_b32 v248, v247
	v_readlane_b32 s96, v246, 1
	v_readlane_b32 s97, v246, 2
	v_mov_b32_e32 v249, 0x39c0
	s_mov_b32 s90, 0
	s_waitcnt lgkmcnt(0)
	v_readfirstlane_b32 s101, v248
	s_nop 3
